# v2_stack plus one s_nop in P8 prologue so P8/P9 K-loop heads return to baseline 8-byte placement
# speedup vs baseline: 1.0184x; 1.0023x over previous
.LBB0_1477:
	s_add_u32 s18, s38, 0x29e00000
	s_addc_u32 s19, s39, 0
	s_add_u32 s20, s38, 0x43900000
	s_addc_u32 s21, s39, 0
	s_add_u32 s22, s36, 0xa848000
	s_addc_u32 s23, s37, 0
	s_ashr_i32 s74, s44, 31
	s_ashr_i32 s75, s2, 31
	s_waitcnt lgkmcnt(0)
	s_add_u32 s24, s12, 0x2c00
	s_addc_u32 s25, s13, 0
	s_add_u32 s26, s12, 0x5800
	s_addc_u32 s27, s13, 0
	s_lshl_b32 s6, s6, 5
	s_mov_b64 s[28:29], 0x80
	s_and_b32 s35, s6, 0x60
	s_add_i32 m0, s49, 0x18000
	v_lshl_add_u64 v[6:7], v[6:7], 0, s[28:29]
	s_lshl_b32 s11, s9, 13
	s_lshl_b32 s30, s35, 7
	s_waitcnt vmcnt(2)
	s_barrier
	global_load_lds_dwordx4 v[6:7], off
	v_lshl_add_u64 v[4:5], v[4:5], 0, s[28:29]
	s_add_i32 m0, s49, 0x1a000
	s_add_i32 s76, s49, 0x8000
	s_add_i32 s77, s49, 0xa000
	global_load_lds_dwordx4 v[4:5], off
	v_lshl_add_u64 v[0:1], v[0:1], 0, s[28:29]
	s_mov_b32 m0, s76
	s_add_u32 s6, s68, 0x40080
	global_load_lds_dwordx4 v[0:1], off
	v_lshl_add_u64 v[0:1], v[2:3], 0, s[28:29]
	s_mov_b32 m0, s77
	s_addc_u32 s7, s69, 0
	global_load_lds_dwordx4 v[0:1], off
	s_add_i32 m0, s49, 0x1c000
	v_lshl_add_u64 v[0:1], s[6:7], 0, v[172:173]
	global_load_lds_dwordx4 v[0:1], off
	v_lshl_add_u64 v[0:1], s[6:7], 0, v[176:177]
	s_add_i32 m0, s49, 0x1e000
	v_lshlrev_b32_e32 v3, 2, v8
	global_load_lds_dwordx4 v[0:1], off
	v_lshrrev_b32_e32 v1, 1, v8
	v_and_b32_e32 v1, 24, v1
	v_and_b32_e32 v0, 15, v8
	v_lshlrev_b32_e32 v2, 1, v1
	v_lshl_or_b32 v2, v0, 6, v2
	v_and_b32_e32 v3, 32, v3
	s_cmpk_lt_u32 s8, 0x100
	v_bitop3_b32 v193, v2, s30, v3 bitop3:0xde
	s_cselect_b64 s[30:31], -1, 0
	s_cmpk_gt_u32 s8, 0xff
	s_cselect_b64 s[40:41], -1, 0
	s_cmp_gt_i32 s9, 2
	v_bitop3_b32 v4, v2, s11, v3 bitop3:0xde
	s_cselect_b64 s[42:43], -1, 0
	s_lshl_b32 s8, s9, 10
	s_add_i32 s11, s9, 2
	s_cmp_gt_i32 s9, 0
	v_lshl_or_b32 v192, s9, 6, v0
	s_cselect_b64 s[52:53], -1, 0
	s_lshl_b32 s9, s11, 10
	s_cmp_lg_u32 s11, 0
	v_or_b32_e32 v194, s35, v1
	s_cselect_b64 s[54:55], -1, 0
	s_add_i32 s11, 0, 0x20000
	v_cmp_lt_u32_e64 s[6:7], 13, v0
	v_add_u32_e32 v178, -14, v0
	v_lshlrev_b32_e32 v0, 9, v0
	s_add_i32 s8, s11, s8
	v_lshlrev_b32_e32 v1, 2, v194
	s_add_i32 s11, s11, s9
	v_add3_u32 v2, s8, v0, v1
	v_add3_u32 v0, s11, v0, v1
	v_add_u32_e32 v198, 0xffffe800, v0
	v_add_u32_e32 v199, 0xffffe810, v0
	v_add_u32_e32 v201, 0xffffe400, v0
	v_lshlrev_b32_e32 v0, 14, v9
	v_and_b32_e32 v0, 0xffff8000, v0
	v_lshl_add_u32 v0, v10, 11, v0
	v_and_b32_e32 v1, 1, v9
	v_lshl_or_b32 v0, v1, 6, v0
	v_lshl_add_u32 v180, v11, 1, v0
	v_lshlrev_b32_e32 v0, 14, v12
	v_and_b32_e32 v0, 0xffff8000, v0
	s_waitcnt vmcnt(6)
	v_lshl_add_u32 v0, v13, 11, v0
	v_and_b32_e32 v1, 1, v12
	v_lshl_or_b32 v0, v1, 6, v0
	s_add_i32 s79, 0, 0x10000
	s_add_i32 s80, 0, 0x14000
	v_mov_b32_e32 v179, v173
	v_add_u32_e32 v195, 0xffffe800, v2
	v_add_u32_e32 v197, 0xffffe810, v2
	v_add_u32_e32 v200, 0xffffe400, v2
	v_mov_b32_e32 v181, v173
	v_lshl_add_u32 v182, v14, 1, v0
	v_mov_b32_e32 v183, v173
	v_mov_b64_e32 v[184:185], 0xb00
	v_mov_b64_e32 v[186:187], 0xaff
	s_movk_i32 s78, 0x161
	v_add_u32_e32 v202, s79, v193
	v_add_u32_e32 v203, s80, v193
	v_add_u32_e32 v204, 0, v4
	s_movk_i32 s81, 0x2c00
	s_movk_i32 s82, 0x1600
	s_nop 0
	s_barrier
	s_branch .LBB0_1480
